# slc loop with stabiliser-free fast body as well (on top of diff fast body, window edits, top-k rewrite)
# speedup vs baseline: 1.0003x; 1.0003x over previous
.Ldiff_fallback:
	s_waitcnt lgkmcnt(0)
	s_mov_b32 s78, 0
	v_mov_b32_e32 v152, 0
	s_branch .Ldiff_redo

.Lslc_fallback:
	s_waitcnt lgkmcnt(0)
	s_mov_b32 s78, 0
	s_mov_b32 s74, 1
	v_mov_b32_e32 v124, 0
	s_branch .LBB0_1328
